# final RMSNorm loop: 4 rows of loads in flight, gain hoisted (plus earlier: early queue pop, combine unroll, lean GEMM1 epilogue)
# speedup vs baseline: 1.0032x; 1.0032x over previous
; __device__ __forceinline__ float bflo(unsigned w) { const f16x2_t b = __builtin_bit_cast(f16x2_t, w); return (float)b[0]; }
; __device__ __forceinline__ float bfhi(unsigned w) { const f16x2_t b = __builtin_bit_cast(f16x2_t, w); return (float)b[1]; }
; __device__ __forceinline__ float row_rstd(const float* part, int row) {
;     const f32x4* p = (const f32x4*)(part + (size_t)row * 16);
;     const f32x4 a = p[0], b = p[1], c = p[2], d = p[3];
;     const float s = (((a[0] + a[1]) + (a[2] + a[3])) + ((b[0] + b[1]) + (b[2] + b[3]))) + (((c[0] + c[1]) + (c[2] + c[3])) + ((d[0] + d[1]) + (d[2] + d[3])));
;     return 1.0f / sqrtf(s * (1.0f / 1024.0f) + 1e-6f);
; }
; __global__ void __launch_bounds__(NTHR, 2) fwd_kernel(Args args) {
;     ...
;     if (PH_ON && !DIS_FIN) {
;         const int gw = blockIdx.x * NWAVES + F.wave, NGW = F.G * NWAVES;
;         for (int m = gw; m < M; m += NGW) { const float rs = pg8::row_rstd(PART, m); f32x4* xr = (f32x4*)(A.out + (size_t)m * DM) + F.lane; const f32x4* gr = (const f32x4*)A.final_norm + F.lane;
;             const u32x2* xb = (const u32x2*)(XN + (size_t)m * DM) + F.lane;
; #pragma unroll
;             for (int j = 0; j < 4; ++j) { const u32x2 b = xb[64 * j]; const f32x4 v = (f32x4){bflo(b.x), bfhi(b.x), bflo(b.y), bfhi(b.y)}, gg = gr[64 * j]; xr[64 * j] = v * rs * gg; } }
.LBB0_1151:
	s_cmp_lt_i32 s76, 26
	s_cselect_b64 s[0:1], -1, 0
	s_cmp_gt_i32 s77, 25
	s_cselect_b64 s[4:5], -1, 0
	s_and_b64 s[0:1], s[0:1], s[4:5]
	s_and_b64 vcc, exec, s[0:1]
	s_cbranch_vccz .LBB0_1155
	s_lshl_b32 s0, s72, 3
	v_readlane_b32 s2, v255, 22
	s_add_i32 s2, s2, s0
	s_cmpk_gt_i32 s2, 0x7fff
	v_readlane_b32 s3, v255, 23
	s_cbranch_scc1 .LBB0_1155
	s_lshl_b32 s4, s78, 3
	s_ashr_i32 s3, s2, 31
	s_ashr_i32 s5, s4, 31
	s_lshl_b64 s[6:7], s[2:3], 6
	s_lshl_b64 s[8:9], s[4:5], 6
	s_lshl_b64 s[0:1], s[2:3], 12
	v_mov_b32_e32 v179, 0
	s_add_u32 s0, s60, s0
	s_waitcnt lgkmcnt(0)
	v_lshlrev_b64 v[2:3], 4, v[178:179]
	s_addc_u32 s1, s61, s1
	v_lshl_add_u64 v[0:1], s[58:59], 0, v[2:3]
	v_lshl_add_u64 v[2:3], s[0:1], 0, v[2:3]
	s_mov_b64 s[0:1], 0xc00
	v_lshl_add_u64 v[2:3], v[2:3], 0, s[0:1]
	s_lshl_b64 s[0:1], s[2:3], 11
	s_lshl_b64 s[10:11], s[4:5], 12
	s_waitcnt vmcnt(0)
	v_lshl_add_u64 v[4:5], v[178:179], 3, s[0:1]
	s_lshl_b64 s[12:13], s[4:5], 11
	v_mov_b32_e32 v6, 0x300000
	v_mov_b32_e32 v7, 0x358637bd
	s_mov_b32 s3, 0xf800000
	v_mov_b32_e32 v8, 0x260
	s_mov_b32 s5, 0x5800000
	global_load_dwordx4 v[40:43], v[0:1], off
	global_load_dwordx4 v[44:47], v[0:1], off offset:1024
	global_load_dwordx4 v[48:51], v[0:1], off offset:2048
	global_load_dwordx4 v[52:55], v[0:1], off offset:3072
	v_lshl_add_u64 v[56:57], s[62:63], 0, v[4:5]
	v_add_co_u32_e32 v56, vcc, s5, v56
	s_nop 1
	v_addc_co_u32_e32 v57, vcc, 0, v57, vcc
.LBB0_1154:
	s_add_u32 s14, s62, s6
	s_addc_u32 s15, s63, s7
	global_load_dwordx4 v[64:67], v6, s[14:15]
	global_load_dwordx4 v[68:71], v6, s[14:15] offset:16
	global_load_dwordx4 v[72:75], v6, s[14:15] offset:32
	global_load_dwordx4 v[76:79], v6, s[14:15] offset:48
	global_load_dwordx2 v[80:81], v[56:57], off
	global_load_dwordx2 v[82:83], v[56:57], off offset:512
	global_load_dwordx2 v[84:85], v[56:57], off offset:1024
	global_load_dwordx2 v[86:87], v[56:57], off offset:1536
	s_add_u32 s6, s6, s8
	s_addc_u32 s7, s7, s9
	v_lshl_add_u64 v[56:57], v[56:57], 0, s[12:13]
	s_add_u32 s14, s62, s6
	s_addc_u32 s15, s63, s7
	global_load_dwordx4 v[88:91], v6, s[14:15]
	global_load_dwordx4 v[92:95], v6, s[14:15] offset:16
	global_load_dwordx4 v[96:99], v6, s[14:15] offset:32
	global_load_dwordx4 v[100:103], v6, s[14:15] offset:48
	global_load_dwordx2 v[104:105], v[56:57], off
	global_load_dwordx2 v[106:107], v[56:57], off offset:512
	global_load_dwordx2 v[108:109], v[56:57], off offset:1024
	global_load_dwordx2 v[110:111], v[56:57], off offset:1536
	s_add_u32 s6, s6, s8
	s_addc_u32 s7, s7, s9
	v_lshl_add_u64 v[56:57], v[56:57], 0, s[12:13]
	s_add_u32 s14, s62, s6
	s_addc_u32 s15, s63, s7
	global_load_dwordx4 v[112:115], v6, s[14:15]
	global_load_dwordx4 v[116:119], v6, s[14:15] offset:16
	global_load_dwordx4 v[120:123], v6, s[14:15] offset:32
	global_load_dwordx4 v[124:127], v6, s[14:15] offset:48
	global_load_dwordx2 v[128:129], v[56:57], off
	global_load_dwordx2 v[130:131], v[56:57], off offset:512
	global_load_dwordx2 v[132:133], v[56:57], off offset:1024
	global_load_dwordx2 v[134:135], v[56:57], off offset:1536
	s_add_u32 s6, s6, s8
	s_addc_u32 s7, s7, s9
	v_lshl_add_u64 v[56:57], v[56:57], 0, s[12:13]
	s_add_u32 s14, s62, s6
	s_addc_u32 s15, s63, s7
	global_load_dwordx4 v[136:139], v6, s[14:15]
	global_load_dwordx4 v[140:143], v6, s[14:15] offset:16
	global_load_dwordx4 v[144:147], v6, s[14:15] offset:32
	global_load_dwordx4 v[148:151], v6, s[14:15] offset:48
	global_load_dwordx2 v[152:153], v[56:57], off
	global_load_dwordx2 v[154:155], v[56:57], off offset:512
	global_load_dwordx2 v[156:157], v[56:57], off offset:1024
	global_load_dwordx2 v[158:159], v[56:57], off offset:1536
	s_add_u32 s6, s6, s8
	s_addc_u32 s7, s7, s9
	v_lshl_add_u64 v[56:57], v[56:57], 0, s[12:13]
	s_waitcnt vmcnt(24)
	v_add_f32_e32 v10, v64, v65
	v_add_f32_e32 v11, v66, v67
	v_add_f32_e32 v12, v68, v69
	v_add_f32_e32 v13, v70, v71
	v_add_f32_e32 v14, v72, v73
	v_add_f32_e32 v15, v74, v75
	v_add_f32_e32 v16, v76, v77
	v_add_f32_e32 v17, v78, v79
	v_add_f32_e32 v10, v10, v11
	v_add_f32_e32 v12, v12, v13
	v_add_f32_e32 v14, v14, v15
	v_add_f32_e32 v16, v16, v17
	v_add_f32_e32 v10, v10, v12
	v_add_f32_e32 v14, v14, v16
	v_add_f32_e32 v9, v10, v14
	v_fmamk_f32 v9, v9, 0x3a800000, v7
	v_mul_f32_e32 v10, 0x4f800000, v9
	v_cmp_gt_f32_e32 vcc, s3, v9
	s_nop 1
	v_cndmask_b32_e32 v9, v9, v10, vcc
	v_sqrt_f32_e32 v10, v9
	s_nop 0
	v_add_u32_e32 v11, -1, v10
	v_add_u32_e32 v12, 1, v10
	v_fma_f32 v13, -v11, v10, v9
	v_fma_f32 v14, -v12, v10, v9
	v_cmp_ge_f32_e64 s[0:1], 0, v13
	s_nop 1
	v_cndmask_b32_e64 v10, v10, v11, s[0:1]
	v_cmp_lt_f32_e64 s[0:1], 0, v14
	s_nop 1
	v_cndmask_b32_e64 v10, v10, v12, s[0:1]
	v_mul_f32_e32 v11, 0x37800000, v10
	v_cndmask_b32_e32 v10, v10, v11, vcc
	v_cmp_class_f32_e32 vcc, v9, v8
	s_nop 1
	v_cndmask_b32_e32 v9, v10, v9, vcc
	v_div_scale_f32 v10, s[0:1], v9, v9, 1.0
	v_rcp_f32_e32 v12, v10
	v_div_scale_f32 v11, vcc, 1.0, v9, 1.0
	v_fma_f32 v13, -v10, v12, 1.0
	v_fmac_f32_e32 v12, v13, v12
	v_mul_f32_e32 v13, v11, v12
	v_fma_f32 v14, -v10, v13, v11
	v_fmac_f32_e32 v13, v14, v12
	v_fma_f32 v10, -v10, v13, v11
	v_div_fmas_f32 v10, v10, v12, v13
	v_div_fixup_f32 v14, v10, v9, 1.0
	v_cvt_f32_f16_e32 v16, v80
	v_cvt_f32_f16_sdwa v17, v80 dst_sel:DWORD dst_unused:UNUSED_PAD src0_sel:WORD_1
	v_cvt_f32_f16_e32 v18, v81
	v_cvt_f32_f16_sdwa v19, v81 dst_sel:DWORD dst_unused:UNUSED_PAD src0_sel:WORD_1
	v_pk_mul_f32 v[16:17], v[14:15], v[16:17] op_sel_hi:[0,1]
	v_pk_mul_f32 v[18:19], v[14:15], v[18:19] op_sel_hi:[0,1]
	v_pk_mul_f32 v[20:21], v[40:41], v[16:17]
	v_pk_mul_f32 v[22:23], v[42:43], v[18:19]
	v_cvt_f32_f16_e32 v16, v82
	v_cvt_f32_f16_sdwa v17, v82 dst_sel:DWORD dst_unused:UNUSED_PAD src0_sel:WORD_1
	v_cvt_f32_f16_e32 v18, v83
	v_cvt_f32_f16_sdwa v19, v83 dst_sel:DWORD dst_unused:UNUSED_PAD src0_sel:WORD_1
	v_pk_mul_f32 v[16:17], v[14:15], v[16:17] op_sel_hi:[0,1]
	v_pk_mul_f32 v[18:19], v[14:15], v[18:19] op_sel_hi:[0,1]
	v_pk_mul_f32 v[24:25], v[44:45], v[16:17]
	v_pk_mul_f32 v[26:27], v[46:47], v[18:19]
	v_cvt_f32_f16_e32 v16, v84
	v_cvt_f32_f16_sdwa v17, v84 dst_sel:DWORD dst_unused:UNUSED_PAD src0_sel:WORD_1
	v_cvt_f32_f16_e32 v18, v85
	v_cvt_f32_f16_sdwa v19, v85 dst_sel:DWORD dst_unused:UNUSED_PAD src0_sel:WORD_1
	v_pk_mul_f32 v[16:17], v[14:15], v[16:17] op_sel_hi:[0,1]
	v_pk_mul_f32 v[18:19], v[14:15], v[18:19] op_sel_hi:[0,1]
	v_pk_mul_f32 v[28:29], v[48:49], v[16:17]
	v_pk_mul_f32 v[30:31], v[50:51], v[18:19]
	v_cvt_f32_f16_e32 v16, v86
	v_cvt_f32_f16_sdwa v17, v86 dst_sel:DWORD dst_unused:UNUSED_PAD src0_sel:WORD_1
	v_cvt_f32_f16_e32 v18, v87
	v_cvt_f32_f16_sdwa v19, v87 dst_sel:DWORD dst_unused:UNUSED_PAD src0_sel:WORD_1
	v_pk_mul_f32 v[16:17], v[14:15], v[16:17] op_sel_hi:[0,1]
	v_pk_mul_f32 v[18:19], v[14:15], v[18:19] op_sel_hi:[0,1]
	v_pk_mul_f32 v[32:33], v[52:53], v[16:17]
	v_pk_mul_f32 v[34:35], v[54:55], v[18:19]
	s_cmp_lt_i32 s2, 0x8000
	s_cbranch_scc0 .Lfin_skip0
; __device__ __forceinline__ float bflo(unsigned w) { const f16x2_t b = __builtin_bit_cast(f16x2_t, w); return (float)b[0]; }
; __device__ __forceinline__ float bfhi(unsigned w) { const f16x2_t b = __builtin_bit_cast(f16x2_t, w); return (float)b[1]; }
; __device__ __forceinline__ float row_rstd(const float* part, int row) {
;     const f32x4* p = (const f32x4*)(part + (size_t)row * 16);
;     const f32x4 a = p[0], b = p[1], c = p[2], d = p[3];
;     const float s = (((a[0] + a[1]) + (a[2] + a[3])) + ((b[0] + b[1]) + (b[2] + b[3]))) + (((c[0] + c[1]) + (c[2] + c[3])) + ((d[0] + d[1]) + (d[2] + d[3])));
;     return 1.0f / sqrtf(s * (1.0f / 1024.0f) + 1e-6f);
; }
; __global__ void __launch_bounds__(NTHR, 2) fwd_kernel(Args args) {
;     ...
;         for (int m = gw; m < M; m += NGW) { const float rs = pg8::row_rstd(PART, m); f32x4* xr = (f32x4*)(A.out + (size_t)m * DM) + F.lane; const f32x4* gr = (const f32x4*)A.final_norm + F.lane;
;             const u32x2* xb = (const u32x2*)(XN + (size_t)m * DM) + F.lane;
; #pragma unroll
;             for (int j = 0; j < 4; ++j) { const u32x2 b = xb[64 * j]; const f32x4 v = (f32x4){bflo(b.x), bfhi(b.x), bflo(b.y), bfhi(b.y)}, gg = gr[64 * j]; xr[64 * j] = v * rs * gg; } }
	global_store_dwordx4 v[2:3], v[20:23], off offset:-3072
	global_store_dwordx4 v[2:3], v[24:27], off offset:-2048
	global_store_dwordx4 v[2:3], v[28:31], off offset:-1024
	global_store_dwordx4 v[2:3], v[32:35], off
.Lfin_skip0:
	s_add_i32 s2, s2, s4
	v_lshl_add_u64 v[2:3], v[2:3], 0, s[10:11]
	s_waitcnt vmcnt(20)
	v_add_f32_e32 v10, v88, v89
	v_add_f32_e32 v11, v90, v91
	v_add_f32_e32 v12, v92, v93
	v_add_f32_e32 v13, v94, v95
	v_add_f32_e32 v14, v96, v97
	v_add_f32_e32 v15, v98, v99
	v_add_f32_e32 v16, v100, v101
	v_add_f32_e32 v17, v102, v103
	v_add_f32_e32 v10, v10, v11
	v_add_f32_e32 v12, v12, v13
	v_add_f32_e32 v14, v14, v15
	v_add_f32_e32 v16, v16, v17
	v_add_f32_e32 v10, v10, v12
	v_add_f32_e32 v14, v14, v16
	v_add_f32_e32 v9, v10, v14
	v_fmamk_f32 v9, v9, 0x3a800000, v7
	v_mul_f32_e32 v10, 0x4f800000, v9
	v_cmp_gt_f32_e32 vcc, s3, v9
	s_nop 1
	v_cndmask_b32_e32 v9, v9, v10, vcc
	v_sqrt_f32_e32 v10, v9
	s_nop 0
	v_add_u32_e32 v11, -1, v10
	v_add_u32_e32 v12, 1, v10
	v_fma_f32 v13, -v11, v10, v9
	v_fma_f32 v14, -v12, v10, v9
	v_cmp_ge_f32_e64 s[0:1], 0, v13
	s_nop 1
	v_cndmask_b32_e64 v10, v10, v11, s[0:1]
	v_cmp_lt_f32_e64 s[0:1], 0, v14
	s_nop 1
	v_cndmask_b32_e64 v10, v10, v12, s[0:1]
	v_mul_f32_e32 v11, 0x37800000, v10
	v_cndmask_b32_e32 v10, v10, v11, vcc
	v_cmp_class_f32_e32 vcc, v9, v8
	s_nop 1
	v_cndmask_b32_e32 v9, v10, v9, vcc
	v_div_scale_f32 v10, s[0:1], v9, v9, 1.0
	v_rcp_f32_e32 v12, v10
	v_div_scale_f32 v11, vcc, 1.0, v9, 1.0
	v_fma_f32 v13, -v10, v12, 1.0
	v_fmac_f32_e32 v12, v13, v12
	v_mul_f32_e32 v13, v11, v12
	v_fma_f32 v14, -v10, v13, v11
	v_fmac_f32_e32 v13, v14, v12
	v_fma_f32 v10, -v10, v13, v11
	v_div_fmas_f32 v10, v10, v12, v13
	v_div_fixup_f32 v14, v10, v9, 1.0
	v_cvt_f32_f16_e32 v16, v104
	v_cvt_f32_f16_sdwa v17, v104 dst_sel:DWORD dst_unused:UNUSED_PAD src0_sel:WORD_1
	v_cvt_f32_f16_e32 v18, v105
	v_cvt_f32_f16_sdwa v19, v105 dst_sel:DWORD dst_unused:UNUSED_PAD src0_sel:WORD_1
	v_pk_mul_f32 v[16:17], v[14:15], v[16:17] op_sel_hi:[0,1]
	v_pk_mul_f32 v[18:19], v[14:15], v[18:19] op_sel_hi:[0,1]
	v_pk_mul_f32 v[20:21], v[40:41], v[16:17]
	v_pk_mul_f32 v[22:23], v[42:43], v[18:19]
	v_cvt_f32_f16_e32 v16, v106
	v_cvt_f32_f16_sdwa v17, v106 dst_sel:DWORD dst_unused:UNUSED_PAD src0_sel:WORD_1
	v_cvt_f32_f16_e32 v18, v107
	v_cvt_f32_f16_sdwa v19, v107 dst_sel:DWORD dst_unused:UNUSED_PAD src0_sel:WORD_1
	v_pk_mul_f32 v[16:17], v[14:15], v[16:17] op_sel_hi:[0,1]
	v_pk_mul_f32 v[18:19], v[14:15], v[18:19] op_sel_hi:[0,1]
	v_pk_mul_f32 v[24:25], v[44:45], v[16:17]
	v_pk_mul_f32 v[26:27], v[46:47], v[18:19]
	v_cvt_f32_f16_e32 v16, v108
	v_cvt_f32_f16_sdwa v17, v108 dst_sel:DWORD dst_unused:UNUSED_PAD src0_sel:WORD_1
	v_cvt_f32_f16_e32 v18, v109
	v_cvt_f32_f16_sdwa v19, v109 dst_sel:DWORD dst_unused:UNUSED_PAD src0_sel:WORD_1
	v_pk_mul_f32 v[16:17], v[14:15], v[16:17] op_sel_hi:[0,1]
	v_pk_mul_f32 v[18:19], v[14:15], v[18:19] op_sel_hi:[0,1]
	v_pk_mul_f32 v[28:29], v[48:49], v[16:17]
	v_pk_mul_f32 v[30:31], v[50:51], v[18:19]
	v_cvt_f32_f16_e32 v16, v110
	v_cvt_f32_f16_sdwa v17, v110 dst_sel:DWORD dst_unused:UNUSED_PAD src0_sel:WORD_1
	v_cvt_f32_f16_e32 v18, v111
	v_cvt_f32_f16_sdwa v19, v111 dst_sel:DWORD dst_unused:UNUSED_PAD src0_sel:WORD_1
	v_pk_mul_f32 v[16:17], v[14:15], v[16:17] op_sel_hi:[0,1]
	v_pk_mul_f32 v[18:19], v[14:15], v[18:19] op_sel_hi:[0,1]
	v_pk_mul_f32 v[32:33], v[52:53], v[16:17]
	v_pk_mul_f32 v[34:35], v[54:55], v[18:19]
	s_cmp_lt_i32 s2, 0x8000
	s_cbranch_scc0 .Lfin_skip1
	global_store_dwordx4 v[2:3], v[20:23], off offset:-3072
	global_store_dwordx4 v[2:3], v[24:27], off offset:-2048
	global_store_dwordx4 v[2:3], v[28:31], off offset:-1024
	global_store_dwordx4 v[2:3], v[32:35], off
.Lfin_skip1:
	s_add_i32 s2, s2, s4
	v_lshl_add_u64 v[2:3], v[2:3], 0, s[10:11]
	s_waitcnt vmcnt(16)
	v_add_f32_e32 v10, v112, v113
	v_add_f32_e32 v11, v114, v115
	v_add_f32_e32 v12, v116, v117
	v_add_f32_e32 v13, v118, v119
	v_add_f32_e32 v14, v120, v121
	v_add_f32_e32 v15, v122, v123
	v_add_f32_e32 v16, v124, v125
	v_add_f32_e32 v17, v126, v127
	v_add_f32_e32 v10, v10, v11
	v_add_f32_e32 v12, v12, v13
	v_add_f32_e32 v14, v14, v15
	v_add_f32_e32 v16, v16, v17
	v_add_f32_e32 v10, v10, v12
	v_add_f32_e32 v14, v14, v16
	v_add_f32_e32 v9, v10, v14
	v_fmamk_f32 v9, v9, 0x3a800000, v7
	v_mul_f32_e32 v10, 0x4f800000, v9
	v_cmp_gt_f32_e32 vcc, s3, v9
	s_nop 1
	v_cndmask_b32_e32 v9, v9, v10, vcc
	v_sqrt_f32_e32 v10, v9
	s_nop 0
	v_add_u32_e32 v11, -1, v10
	v_add_u32_e32 v12, 1, v10
	v_fma_f32 v13, -v11, v10, v9
	v_fma_f32 v14, -v12, v10, v9
	v_cmp_ge_f32_e64 s[0:1], 0, v13
	s_nop 1
	v_cndmask_b32_e64 v10, v10, v11, s[0:1]
	v_cmp_lt_f32_e64 s[0:1], 0, v14
	s_nop 1
	v_cndmask_b32_e64 v10, v10, v12, s[0:1]
	v_mul_f32_e32 v11, 0x37800000, v10
	v_cndmask_b32_e32 v10, v10, v11, vcc
	v_cmp_class_f32_e32 vcc, v9, v8
	s_nop 1
	v_cndmask_b32_e32 v9, v10, v9, vcc
	v_div_scale_f32 v10, s[0:1], v9, v9, 1.0
	v_rcp_f32_e32 v12, v10
	v_div_scale_f32 v11, vcc, 1.0, v9, 1.0
	v_fma_f32 v13, -v10, v12, 1.0
	v_fmac_f32_e32 v12, v13, v12
	v_mul_f32_e32 v13, v11, v12
	v_fma_f32 v14, -v10, v13, v11
	v_fmac_f32_e32 v13, v14, v12
	v_fma_f32 v10, -v10, v13, v11
	v_div_fmas_f32 v10, v10, v12, v13
	v_div_fixup_f32 v14, v10, v9, 1.0
	v_cvt_f32_f16_e32 v16, v128
	v_cvt_f32_f16_sdwa v17, v128 dst_sel:DWORD dst_unused:UNUSED_PAD src0_sel:WORD_1
	v_cvt_f32_f16_e32 v18, v129
	v_cvt_f32_f16_sdwa v19, v129 dst_sel:DWORD dst_unused:UNUSED_PAD src0_sel:WORD_1
	v_pk_mul_f32 v[16:17], v[14:15], v[16:17] op_sel_hi:[0,1]
	v_pk_mul_f32 v[18:19], v[14:15], v[18:19] op_sel_hi:[0,1]
	v_pk_mul_f32 v[20:21], v[40:41], v[16:17]
	v_pk_mul_f32 v[22:23], v[42:43], v[18:19]
	v_cvt_f32_f16_e32 v16, v130
	v_cvt_f32_f16_sdwa v17, v130 dst_sel:DWORD dst_unused:UNUSED_PAD src0_sel:WORD_1
	v_cvt_f32_f16_e32 v18, v131
	v_cvt_f32_f16_sdwa v19, v131 dst_sel:DWORD dst_unused:UNUSED_PAD src0_sel:WORD_1
	v_pk_mul_f32 v[16:17], v[14:15], v[16:17] op_sel_hi:[0,1]
	v_pk_mul_f32 v[18:19], v[14:15], v[18:19] op_sel_hi:[0,1]
	v_pk_mul_f32 v[24:25], v[44:45], v[16:17]
	v_pk_mul_f32 v[26:27], v[46:47], v[18:19]
	v_cvt_f32_f16_e32 v16, v132
	v_cvt_f32_f16_sdwa v17, v132 dst_sel:DWORD dst_unused:UNUSED_PAD src0_sel:WORD_1
	v_cvt_f32_f16_e32 v18, v133
	v_cvt_f32_f16_sdwa v19, v133 dst_sel:DWORD dst_unused:UNUSED_PAD src0_sel:WORD_1
	v_pk_mul_f32 v[16:17], v[14:15], v[16:17] op_sel_hi:[0,1]
	v_pk_mul_f32 v[18:19], v[14:15], v[18:19] op_sel_hi:[0,1]
	v_pk_mul_f32 v[28:29], v[48:49], v[16:17]
	v_pk_mul_f32 v[30:31], v[50:51], v[18:19]
	v_cvt_f32_f16_e32 v16, v134
	v_cvt_f32_f16_sdwa v17, v134 dst_sel:DWORD dst_unused:UNUSED_PAD src0_sel:WORD_1
	v_cvt_f32_f16_e32 v18, v135
	v_cvt_f32_f16_sdwa v19, v135 dst_sel:DWORD dst_unused:UNUSED_PAD src0_sel:WORD_1
	v_pk_mul_f32 v[16:17], v[14:15], v[16:17] op_sel_hi:[0,1]
	v_pk_mul_f32 v[18:19], v[14:15], v[18:19] op_sel_hi:[0,1]
	v_pk_mul_f32 v[32:33], v[52:53], v[16:17]
	v_pk_mul_f32 v[34:35], v[54:55], v[18:19]
	s_cmp_lt_i32 s2, 0x8000
	s_cbranch_scc0 .Lfin_skip2
; __device__ __forceinline__ float bflo(unsigned w) { const f16x2_t b = __builtin_bit_cast(f16x2_t, w); return (float)b[0]; }
; __device__ __forceinline__ float bfhi(unsigned w) { const f16x2_t b = __builtin_bit_cast(f16x2_t, w); return (float)b[1]; }
; __global__ void __launch_bounds__(NTHR, 2) fwd_kernel(Args args) {
;     ...
;         for (int m = gw; m < M; m += NGW) { const float rs = pg8::row_rstd(PART, m); f32x4* xr = (f32x4*)(A.out + (size_t)m * DM) + F.lane; const f32x4* gr = (const f32x4*)A.final_norm + F.lane;
;             const u32x2* xb = (const u32x2*)(XN + (size_t)m * DM) + F.lane;
; #pragma unroll
;             for (int j = 0; j < 4; ++j) { const u32x2 b = xb[64 * j]; const f32x4 v = (f32x4){bflo(b.x), bfhi(b.x), bflo(b.y), bfhi(b.y)}, gg = gr[64 * j]; xr[64 * j] = v * rs * gg; } }
	global_store_dwordx4 v[2:3], v[20:23], off offset:-3072
	global_store_dwordx4 v[2:3], v[24:27], off offset:-2048
	global_store_dwordx4 v[2:3], v[28:31], off offset:-1024
	global_store_dwordx4 v[2:3], v[32:35], off
.Lfin_skip2:
	s_add_i32 s2, s2, s4
	v_lshl_add_u64 v[2:3], v[2:3], 0, s[10:11]
	s_waitcnt vmcnt(12)
	v_add_f32_e32 v10, v136, v137
	v_add_f32_e32 v11, v138, v139
	v_add_f32_e32 v12, v140, v141
	v_add_f32_e32 v13, v142, v143
	v_add_f32_e32 v14, v144, v145
	v_add_f32_e32 v15, v146, v147
	v_add_f32_e32 v16, v148, v149
	v_add_f32_e32 v17, v150, v151
	v_add_f32_e32 v10, v10, v11
	v_add_f32_e32 v12, v12, v13
	v_add_f32_e32 v14, v14, v15
	v_add_f32_e32 v16, v16, v17
	v_add_f32_e32 v10, v10, v12
	v_add_f32_e32 v14, v14, v16
	v_add_f32_e32 v9, v10, v14
	v_fmamk_f32 v9, v9, 0x3a800000, v7
	v_mul_f32_e32 v10, 0x4f800000, v9
	v_cmp_gt_f32_e32 vcc, s3, v9
	s_nop 1
	v_cndmask_b32_e32 v9, v9, v10, vcc
	v_sqrt_f32_e32 v10, v9
	s_nop 0
	v_add_u32_e32 v11, -1, v10
	v_add_u32_e32 v12, 1, v10
	v_fma_f32 v13, -v11, v10, v9
	v_fma_f32 v14, -v12, v10, v9
	v_cmp_ge_f32_e64 s[0:1], 0, v13
	s_nop 1
	v_cndmask_b32_e64 v10, v10, v11, s[0:1]
	v_cmp_lt_f32_e64 s[0:1], 0, v14
	s_nop 1
	v_cndmask_b32_e64 v10, v10, v12, s[0:1]
	v_mul_f32_e32 v11, 0x37800000, v10
	v_cndmask_b32_e32 v10, v10, v11, vcc
	v_cmp_class_f32_e32 vcc, v9, v8
	s_nop 1
	v_cndmask_b32_e32 v9, v10, v9, vcc
	v_div_scale_f32 v10, s[0:1], v9, v9, 1.0
	v_rcp_f32_e32 v12, v10
	v_div_scale_f32 v11, vcc, 1.0, v9, 1.0
	v_fma_f32 v13, -v10, v12, 1.0
	v_fmac_f32_e32 v12, v13, v12
	v_mul_f32_e32 v13, v11, v12
	v_fma_f32 v14, -v10, v13, v11
	v_fmac_f32_e32 v13, v14, v12
	v_fma_f32 v10, -v10, v13, v11
	v_div_fmas_f32 v10, v10, v12, v13
	v_div_fixup_f32 v14, v10, v9, 1.0
	v_cvt_f32_f16_e32 v16, v152
	v_cvt_f32_f16_sdwa v17, v152 dst_sel:DWORD dst_unused:UNUSED_PAD src0_sel:WORD_1
	v_cvt_f32_f16_e32 v18, v153
	v_cvt_f32_f16_sdwa v19, v153 dst_sel:DWORD dst_unused:UNUSED_PAD src0_sel:WORD_1
	v_pk_mul_f32 v[16:17], v[14:15], v[16:17] op_sel_hi:[0,1]
	v_pk_mul_f32 v[18:19], v[14:15], v[18:19] op_sel_hi:[0,1]
	v_pk_mul_f32 v[20:21], v[40:41], v[16:17]
	v_pk_mul_f32 v[22:23], v[42:43], v[18:19]
	v_cvt_f32_f16_e32 v16, v154
	v_cvt_f32_f16_sdwa v17, v154 dst_sel:DWORD dst_unused:UNUSED_PAD src0_sel:WORD_1
	v_cvt_f32_f16_e32 v18, v155
	v_cvt_f32_f16_sdwa v19, v155 dst_sel:DWORD dst_unused:UNUSED_PAD src0_sel:WORD_1
	v_pk_mul_f32 v[16:17], v[14:15], v[16:17] op_sel_hi:[0,1]
	v_pk_mul_f32 v[18:19], v[14:15], v[18:19] op_sel_hi:[0,1]
	v_pk_mul_f32 v[24:25], v[44:45], v[16:17]
	v_pk_mul_f32 v[26:27], v[46:47], v[18:19]
	v_cvt_f32_f16_e32 v16, v156
	v_cvt_f32_f16_sdwa v17, v156 dst_sel:DWORD dst_unused:UNUSED_PAD src0_sel:WORD_1
	v_cvt_f32_f16_e32 v18, v157
	v_cvt_f32_f16_sdwa v19, v157 dst_sel:DWORD dst_unused:UNUSED_PAD src0_sel:WORD_1
	v_pk_mul_f32 v[16:17], v[14:15], v[16:17] op_sel_hi:[0,1]
	v_pk_mul_f32 v[18:19], v[14:15], v[18:19] op_sel_hi:[0,1]
	v_pk_mul_f32 v[28:29], v[48:49], v[16:17]
	v_pk_mul_f32 v[30:31], v[50:51], v[18:19]
	v_cvt_f32_f16_e32 v16, v158
	v_cvt_f32_f16_sdwa v17, v158 dst_sel:DWORD dst_unused:UNUSED_PAD src0_sel:WORD_1
	v_cvt_f32_f16_e32 v18, v159
	v_cvt_f32_f16_sdwa v19, v159 dst_sel:DWORD dst_unused:UNUSED_PAD src0_sel:WORD_1
	v_pk_mul_f32 v[16:17], v[14:15], v[16:17] op_sel_hi:[0,1]
	v_pk_mul_f32 v[18:19], v[14:15], v[18:19] op_sel_hi:[0,1]
	v_pk_mul_f32 v[32:33], v[52:53], v[16:17]
	v_pk_mul_f32 v[34:35], v[54:55], v[18:19]
	s_cmp_lt_i32 s2, 0x8000
	s_cbranch_scc0 .Lfin_skip3
	global_store_dwordx4 v[2:3], v[20:23], off offset:-3072
	global_store_dwordx4 v[2:3], v[24:27], off offset:-2048
	global_store_dwordx4 v[2:3], v[28:31], off offset:-1024
	global_store_dwordx4 v[2:3], v[32:35], off
.Lfin_skip3:
	s_add_i32 s2, s2, s4
	v_lshl_add_u64 v[2:3], v[2:3], 0, s[10:11]
	s_cmp_lt_i32 s2, 0x8000
	s_cbranch_scc1 .LBB0_1154
